# SWIGLU epilogue: batched silu with v_rcp_f32 (f32) instead of 64 serial IEEE division sequences, saddr global stores, no store drain before next unit row-sum loads
# speedup vs baseline: 1.0656x; 1.0214x over previous
; __device__ __forceinline__ unsigned cvt_pk_bf16(float lo, float hi) { f32x2 v = {lo, hi}; bf16x2_t b = __builtin_convertvector(v, bf16x2_t); return __builtin_bit_cast(unsigned, b); }
; __device__ __forceinline__ float siluf(float v) { return v / (1.f + __expf(-v)); }
; template <int MODE> __device__ __forceinline__ void gemm_epilogue(f32x4 (&acc)[2][2][4][2], const GD& g, const pg8::Unit& u, int wr, int wc, int fr, int fq, LAS unsigned char* lds, const float (&rsv)[2][4]) {
;     ...
;     } else if constexpr (MODE == EP_SWIGLU) {
;         bf16_t* O = (bf16_t*)g.o0; const int col0 = u.pn * 128 + ct;
; #pragma unroll
;         for (int ai = 0; ai < 2; ++ai)
; #pragma unroll
;             for (int m = 0; m < 4; ++m) { const f32x4 g0 = acc[ai][0][m][0], g1 = acc[ai][0][m][1], u0 = acc[ai][1][m][0], u1 = acc[ai][1][m][1]; f32x4 h0, h1;
; #pragma unroll
;                 for (int j = 0; j < 4; ++j) { h0[j] = siluf(g0[j]) * u0[j]; h1[j] = siluf(g1[j]) * u1[j]; }
;                 u32x4 w; w.x = cvt_pk_bf16(h0[0], h0[1]); w.y = cvt_pk_bf16(h0[2], h0[3]); w.z = cvt_pk_bf16(h1[0], h1[1]); w.w = cvt_pk_bf16(h1[2], h1[3]);
;                 *(u32x4*)(O + (size_t)(rt + ai * 128 + m * 16) * DFF + col0) = w; }
.LBB0_134:
	v_lshl_add_u32 v1, s1, 8, v144
	v_lshl_or_b32 v157, s0, 7, v154
	v_readlane_b32 s0, v254, 42
	v_readlane_b32 s1, v254, 43
	v_mul_u32_u24_e32 v1, 0x2c00, v1
	v_mov_b32_e32 v142, 0xbfb8aa3b
	v_mov_b32_e32 v143, 0xbfb8aa3b
	s_mov_b64 s[2:3], -1
	v_lshl_add_u32 v1, v157, 1, v1
	v_pk_mul_f32 v[158:159], v[126:127], v[142:143]
	v_pk_mul_f32 v[160:161], v[128:129], v[142:143]
	v_pk_mul_f32 v[162:163], v[118:119], v[142:143]
	v_pk_mul_f32 v[164:165], v[120:121], v[142:143]
	v_exp_f32_e32 v158, v158
	v_exp_f32_e32 v159, v159
	v_exp_f32_e32 v160, v160
	v_exp_f32_e32 v161, v161
	v_exp_f32_e32 v162, v162
	v_exp_f32_e32 v163, v163
	v_exp_f32_e32 v164, v164
	v_exp_f32_e32 v165, v165
	v_pk_add_f32 v[158:159], v[158:159], 1.0 op_sel_hi:[1,0]
	v_pk_add_f32 v[160:161], v[160:161], 1.0 op_sel_hi:[1,0]
	v_pk_add_f32 v[162:163], v[162:163], 1.0 op_sel_hi:[1,0]
	v_pk_add_f32 v[164:165], v[164:165], 1.0 op_sel_hi:[1,0]
	v_rcp_f32_e32 v158, v158
	v_rcp_f32_e32 v159, v159
	v_rcp_f32_e32 v160, v160
	v_rcp_f32_e32 v161, v161
	v_rcp_f32_e32 v162, v162
	v_rcp_f32_e32 v163, v163
	v_rcp_f32_e32 v164, v164
	v_rcp_f32_e32 v165, v165
	v_pk_mul_f32 v[158:159], v[158:159], v[126:127]
	v_pk_mul_f32 v[160:161], v[160:161], v[128:129]
	v_pk_mul_f32 v[162:163], v[162:163], v[118:119]
	v_pk_mul_f32 v[164:165], v[164:165], v[120:121]
	v_pk_mul_f32 v[158:159], v[158:159], v[122:123]
	v_pk_mul_f32 v[160:161], v[160:161], v[124:125]
	v_pk_mul_f32 v[162:163], v[162:163], v[114:115]
	v_pk_mul_f32 v[164:165], v[164:165], v[116:117]
	v_cvt_pk_bf16_f32 v166, v158, v159
	v_cvt_pk_bf16_f32 v167, v160, v161
	v_cvt_pk_bf16_f32 v168, v162, v163
	v_cvt_pk_bf16_f32 v169, v164, v165
	global_store_dwordx4 v1, v[166:169], s[0:1]
	v_add_u32_e32 v1, 0x2c000, v1
	v_pk_mul_f32 v[158:159], v[110:111], v[142:143]
	v_pk_mul_f32 v[160:161], v[112:113], v[142:143]
	v_pk_mul_f32 v[162:163], v[102:103], v[142:143]
	v_pk_mul_f32 v[164:165], v[104:105], v[142:143]
	v_exp_f32_e32 v158, v158
	v_exp_f32_e32 v159, v159
	v_exp_f32_e32 v160, v160
	v_exp_f32_e32 v161, v161
	v_exp_f32_e32 v162, v162
	v_exp_f32_e32 v163, v163
	v_exp_f32_e32 v164, v164
	v_exp_f32_e32 v165, v165
	v_pk_add_f32 v[158:159], v[158:159], 1.0 op_sel_hi:[1,0]
	v_pk_add_f32 v[160:161], v[160:161], 1.0 op_sel_hi:[1,0]
	v_pk_add_f32 v[162:163], v[162:163], 1.0 op_sel_hi:[1,0]
	v_pk_add_f32 v[164:165], v[164:165], 1.0 op_sel_hi:[1,0]
	v_rcp_f32_e32 v158, v158
	v_rcp_f32_e32 v159, v159
	v_rcp_f32_e32 v160, v160
	v_rcp_f32_e32 v161, v161
	v_rcp_f32_e32 v162, v162
	v_rcp_f32_e32 v163, v163
	v_rcp_f32_e32 v164, v164
	v_rcp_f32_e32 v165, v165
	v_pk_mul_f32 v[158:159], v[158:159], v[110:111]
	v_pk_mul_f32 v[160:161], v[160:161], v[112:113]
	v_pk_mul_f32 v[162:163], v[162:163], v[102:103]
	v_pk_mul_f32 v[164:165], v[164:165], v[104:105]
	v_pk_mul_f32 v[158:159], v[158:159], v[106:107]
	v_pk_mul_f32 v[160:161], v[160:161], v[108:109]
	v_pk_mul_f32 v[162:163], v[162:163], v[98:99]
	v_pk_mul_f32 v[164:165], v[164:165], v[100:101]
	v_cvt_pk_bf16_f32 v166, v158, v159
	v_cvt_pk_bf16_f32 v167, v160, v161
	v_cvt_pk_bf16_f32 v168, v162, v163
	v_cvt_pk_bf16_f32 v169, v164, v165
	global_store_dwordx4 v1, v[166:169], s[0:1]
	v_add_u32_e32 v1, 0x2c000, v1
	v_pk_mul_f32 v[158:159], v[94:95], v[142:143]
	v_pk_mul_f32 v[160:161], v[96:97], v[142:143]
	v_pk_mul_f32 v[162:163], v[86:87], v[142:143]
	v_pk_mul_f32 v[164:165], v[88:89], v[142:143]
	v_exp_f32_e32 v158, v158
	v_exp_f32_e32 v159, v159
	v_exp_f32_e32 v160, v160
	v_exp_f32_e32 v161, v161
	v_exp_f32_e32 v162, v162
	v_exp_f32_e32 v163, v163
	v_exp_f32_e32 v164, v164
	v_exp_f32_e32 v165, v165
	v_pk_add_f32 v[158:159], v[158:159], 1.0 op_sel_hi:[1,0]
	v_pk_add_f32 v[160:161], v[160:161], 1.0 op_sel_hi:[1,0]
	v_pk_add_f32 v[162:163], v[162:163], 1.0 op_sel_hi:[1,0]
	v_pk_add_f32 v[164:165], v[164:165], 1.0 op_sel_hi:[1,0]
	v_rcp_f32_e32 v158, v158
	v_rcp_f32_e32 v159, v159
	v_rcp_f32_e32 v160, v160
	v_rcp_f32_e32 v161, v161
	v_rcp_f32_e32 v162, v162
	v_rcp_f32_e32 v163, v163
	v_rcp_f32_e32 v164, v164
	v_rcp_f32_e32 v165, v165
	v_pk_mul_f32 v[158:159], v[158:159], v[94:95]
	v_pk_mul_f32 v[160:161], v[160:161], v[96:97]
	v_pk_mul_f32 v[162:163], v[162:163], v[86:87]
	v_pk_mul_f32 v[164:165], v[164:165], v[88:89]
	v_pk_mul_f32 v[158:159], v[158:159], v[90:91]
	v_pk_mul_f32 v[160:161], v[160:161], v[92:93]
	v_pk_mul_f32 v[162:163], v[162:163], v[82:83]
	v_pk_mul_f32 v[164:165], v[164:165], v[84:85]
	v_cvt_pk_bf16_f32 v166, v158, v159
	v_cvt_pk_bf16_f32 v167, v160, v161
	v_cvt_pk_bf16_f32 v168, v162, v163
	v_cvt_pk_bf16_f32 v169, v164, v165
	global_store_dwordx4 v1, v[166:169], s[0:1]
	v_add_u32_e32 v1, 0x2c000, v1
	v_pk_mul_f32 v[158:159], v[78:79], v[142:143]
	v_pk_mul_f32 v[160:161], v[80:81], v[142:143]
	v_pk_mul_f32 v[162:163], v[70:71], v[142:143]
	v_pk_mul_f32 v[164:165], v[72:73], v[142:143]
	v_exp_f32_e32 v158, v158
	v_exp_f32_e32 v159, v159
	v_exp_f32_e32 v160, v160
	v_exp_f32_e32 v161, v161
	v_exp_f32_e32 v162, v162
	v_exp_f32_e32 v163, v163
	v_exp_f32_e32 v164, v164
	v_exp_f32_e32 v165, v165
	v_pk_add_f32 v[158:159], v[158:159], 1.0 op_sel_hi:[1,0]
	v_pk_add_f32 v[160:161], v[160:161], 1.0 op_sel_hi:[1,0]
	v_pk_add_f32 v[162:163], v[162:163], 1.0 op_sel_hi:[1,0]
	v_pk_add_f32 v[164:165], v[164:165], 1.0 op_sel_hi:[1,0]
	v_rcp_f32_e32 v158, v158
	v_rcp_f32_e32 v159, v159
	v_rcp_f32_e32 v160, v160
	v_rcp_f32_e32 v161, v161
	v_rcp_f32_e32 v162, v162
	v_rcp_f32_e32 v163, v163
	v_rcp_f32_e32 v164, v164
	v_rcp_f32_e32 v165, v165
	v_pk_mul_f32 v[158:159], v[158:159], v[78:79]
	v_pk_mul_f32 v[160:161], v[160:161], v[80:81]
	v_pk_mul_f32 v[162:163], v[162:163], v[70:71]
	v_pk_mul_f32 v[164:165], v[164:165], v[72:73]
; __device__ __forceinline__ unsigned cvt_pk_bf16(float lo, float hi) { f32x2 v = {lo, hi}; bf16x2_t b = __builtin_convertvector(v, bf16x2_t); return __builtin_bit_cast(unsigned, b); }
; __device__ __forceinline__ float siluf(float v) { return v / (1.f + __expf(-v)); }
; template <int MODE> __device__ __forceinline__ void gemm_epilogue(f32x4 (&acc)[2][2][4][2], const GD& g, const pg8::Unit& u, int wr, int wc, int fr, int fq, LAS unsigned char* lds, const float (&rsv)[2][4]) {
;     ...
;     } else if constexpr (MODE == EP_SWIGLU) {
;         bf16_t* O = (bf16_t*)g.o0; const int col0 = u.pn * 128 + ct;
; #pragma unroll
;         for (int ai = 0; ai < 2; ++ai)
; #pragma unroll
;             for (int m = 0; m < 4; ++m) { const f32x4 g0 = acc[ai][0][m][0], g1 = acc[ai][0][m][1], u0 = acc[ai][1][m][0], u1 = acc[ai][1][m][1]; f32x4 h0, h1;
; #pragma unroll
;                 for (int j = 0; j < 4; ++j) { h0[j] = siluf(g0[j]) * u0[j]; h1[j] = siluf(g1[j]) * u1[j]; }
;                 u32x4 w; w.x = cvt_pk_bf16(h0[0], h0[1]); w.y = cvt_pk_bf16(h0[2], h0[3]); w.z = cvt_pk_bf16(h1[0], h1[1]); w.w = cvt_pk_bf16(h1[2], h1[3]);
;                 *(u32x4*)(O + (size_t)(rt + ai * 128 + m * 16) * DFF + col0) = w; }
	v_pk_mul_f32 v[158:159], v[158:159], v[74:75]
	v_pk_mul_f32 v[160:161], v[160:161], v[76:77]
	v_pk_mul_f32 v[162:163], v[162:163], v[66:67]
	v_pk_mul_f32 v[164:165], v[164:165], v[68:69]
	v_cvt_pk_bf16_f32 v166, v158, v159
	v_cvt_pk_bf16_f32 v167, v160, v161
	v_cvt_pk_bf16_f32 v168, v162, v163
	v_cvt_pk_bf16_f32 v169, v164, v165
	global_store_dwordx4 v1, v[166:169], s[0:1]
	v_add_u32_e32 v1, 0xdc000, v1
	v_pk_mul_f32 v[158:159], v[62:63], v[142:143]
	v_pk_mul_f32 v[160:161], v[64:65], v[142:143]
	v_pk_mul_f32 v[162:163], v[54:55], v[142:143]
	v_pk_mul_f32 v[164:165], v[56:57], v[142:143]
	v_exp_f32_e32 v158, v158
	v_exp_f32_e32 v159, v159
	v_exp_f32_e32 v160, v160
	v_exp_f32_e32 v161, v161
	v_exp_f32_e32 v162, v162
	v_exp_f32_e32 v163, v163
	v_exp_f32_e32 v164, v164
	v_exp_f32_e32 v165, v165
	v_pk_add_f32 v[158:159], v[158:159], 1.0 op_sel_hi:[1,0]
	v_pk_add_f32 v[160:161], v[160:161], 1.0 op_sel_hi:[1,0]
	v_pk_add_f32 v[162:163], v[162:163], 1.0 op_sel_hi:[1,0]
	v_pk_add_f32 v[164:165], v[164:165], 1.0 op_sel_hi:[1,0]
	v_rcp_f32_e32 v158, v158
	v_rcp_f32_e32 v159, v159
	v_rcp_f32_e32 v160, v160
	v_rcp_f32_e32 v161, v161
	v_rcp_f32_e32 v162, v162
	v_rcp_f32_e32 v163, v163
	v_rcp_f32_e32 v164, v164
	v_rcp_f32_e32 v165, v165
	v_pk_mul_f32 v[158:159], v[158:159], v[62:63]
	v_pk_mul_f32 v[160:161], v[160:161], v[64:65]
	v_pk_mul_f32 v[162:163], v[162:163], v[54:55]
	v_pk_mul_f32 v[164:165], v[164:165], v[56:57]
	v_pk_mul_f32 v[158:159], v[158:159], v[58:59]
	v_pk_mul_f32 v[160:161], v[160:161], v[60:61]
	v_pk_mul_f32 v[162:163], v[162:163], v[50:51]
	v_pk_mul_f32 v[164:165], v[164:165], v[52:53]
	v_cvt_pk_bf16_f32 v166, v158, v159
	v_cvt_pk_bf16_f32 v167, v160, v161
	v_cvt_pk_bf16_f32 v168, v162, v163
	v_cvt_pk_bf16_f32 v169, v164, v165
	global_store_dwordx4 v1, v[166:169], s[0:1]
	v_add_u32_e32 v1, 0x2c000, v1
	v_pk_mul_f32 v[158:159], v[46:47], v[142:143]
	v_pk_mul_f32 v[160:161], v[48:49], v[142:143]
	v_pk_mul_f32 v[162:163], v[38:39], v[142:143]
	v_pk_mul_f32 v[164:165], v[40:41], v[142:143]
	v_exp_f32_e32 v158, v158
	v_exp_f32_e32 v159, v159
	v_exp_f32_e32 v160, v160
	v_exp_f32_e32 v161, v161
	v_exp_f32_e32 v162, v162
	v_exp_f32_e32 v163, v163
	v_exp_f32_e32 v164, v164
	v_exp_f32_e32 v165, v165
	v_pk_add_f32 v[158:159], v[158:159], 1.0 op_sel_hi:[1,0]
	v_pk_add_f32 v[160:161], v[160:161], 1.0 op_sel_hi:[1,0]
	v_pk_add_f32 v[162:163], v[162:163], 1.0 op_sel_hi:[1,0]
	v_pk_add_f32 v[164:165], v[164:165], 1.0 op_sel_hi:[1,0]
	v_rcp_f32_e32 v158, v158
	v_rcp_f32_e32 v159, v159
	v_rcp_f32_e32 v160, v160
	v_rcp_f32_e32 v161, v161
	v_rcp_f32_e32 v162, v162
	v_rcp_f32_e32 v163, v163
	v_rcp_f32_e32 v164, v164
	v_rcp_f32_e32 v165, v165
	v_pk_mul_f32 v[158:159], v[158:159], v[46:47]
	v_pk_mul_f32 v[160:161], v[160:161], v[48:49]
	v_pk_mul_f32 v[162:163], v[162:163], v[38:39]
	v_pk_mul_f32 v[164:165], v[164:165], v[40:41]
	v_pk_mul_f32 v[158:159], v[158:159], v[42:43]
	v_pk_mul_f32 v[160:161], v[160:161], v[44:45]
	v_pk_mul_f32 v[162:163], v[162:163], v[34:35]
	v_pk_mul_f32 v[164:165], v[164:165], v[36:37]
	v_cvt_pk_bf16_f32 v166, v158, v159
	v_cvt_pk_bf16_f32 v167, v160, v161
	v_cvt_pk_bf16_f32 v168, v162, v163
	v_cvt_pk_bf16_f32 v169, v164, v165
	global_store_dwordx4 v1, v[166:169], s[0:1]
	v_add_u32_e32 v1, 0x2c000, v1
	v_pk_mul_f32 v[158:159], v[30:31], v[142:143]
	v_pk_mul_f32 v[160:161], v[32:33], v[142:143]
	v_pk_mul_f32 v[162:163], v[22:23], v[142:143]
	v_pk_mul_f32 v[164:165], v[24:25], v[142:143]
	v_exp_f32_e32 v158, v158
	v_exp_f32_e32 v159, v159
	v_exp_f32_e32 v160, v160
	v_exp_f32_e32 v161, v161
	v_exp_f32_e32 v162, v162
	v_exp_f32_e32 v163, v163
	v_exp_f32_e32 v164, v164
	v_exp_f32_e32 v165, v165
	v_pk_add_f32 v[158:159], v[158:159], 1.0 op_sel_hi:[1,0]
	v_pk_add_f32 v[160:161], v[160:161], 1.0 op_sel_hi:[1,0]
	v_pk_add_f32 v[162:163], v[162:163], 1.0 op_sel_hi:[1,0]
	v_pk_add_f32 v[164:165], v[164:165], 1.0 op_sel_hi:[1,0]
	v_rcp_f32_e32 v158, v158
	v_rcp_f32_e32 v159, v159
	v_rcp_f32_e32 v160, v160
	v_rcp_f32_e32 v161, v161
	v_rcp_f32_e32 v162, v162
	v_rcp_f32_e32 v163, v163
	v_rcp_f32_e32 v164, v164
	v_rcp_f32_e32 v165, v165
	v_pk_mul_f32 v[158:159], v[158:159], v[30:31]
	v_pk_mul_f32 v[160:161], v[160:161], v[32:33]
	v_pk_mul_f32 v[162:163], v[162:163], v[22:23]
	v_pk_mul_f32 v[164:165], v[164:165], v[24:25]
	v_pk_mul_f32 v[158:159], v[158:159], v[26:27]
	v_pk_mul_f32 v[160:161], v[160:161], v[28:29]
	v_pk_mul_f32 v[162:163], v[162:163], v[18:19]
	v_pk_mul_f32 v[164:165], v[164:165], v[20:21]
	v_cvt_pk_bf16_f32 v166, v158, v159
	v_cvt_pk_bf16_f32 v167, v160, v161
	v_cvt_pk_bf16_f32 v168, v162, v163
	v_cvt_pk_bf16_f32 v169, v164, v165
	global_store_dwordx4 v1, v[166:169], s[0:1]
	v_add_u32_e32 v1, 0x2c000, v1
	v_pk_mul_f32 v[158:159], v[14:15], v[142:143]
	v_pk_mul_f32 v[160:161], v[16:17], v[142:143]
	v_pk_mul_f32 v[162:163], v[6:7], v[142:143]
	v_pk_mul_f32 v[164:165], v[8:9], v[142:143]
	v_exp_f32_e32 v158, v158
	v_exp_f32_e32 v159, v159
	v_exp_f32_e32 v160, v160
	v_exp_f32_e32 v161, v161
	v_exp_f32_e32 v162, v162
	v_exp_f32_e32 v163, v163
	v_exp_f32_e32 v164, v164
	v_exp_f32_e32 v165, v165
	v_pk_add_f32 v[158:159], v[158:159], 1.0 op_sel_hi:[1,0]
	v_pk_add_f32 v[160:161], v[160:161], 1.0 op_sel_hi:[1,0]
	v_pk_add_f32 v[162:163], v[162:163], 1.0 op_sel_hi:[1,0]
	v_pk_add_f32 v[164:165], v[164:165], 1.0 op_sel_hi:[1,0]
	v_rcp_f32_e32 v158, v158
	v_rcp_f32_e32 v159, v159
	v_rcp_f32_e32 v160, v160
	v_rcp_f32_e32 v161, v161
	v_rcp_f32_e32 v162, v162
	v_rcp_f32_e32 v163, v163
	v_rcp_f32_e32 v164, v164
	v_rcp_f32_e32 v165, v165
	v_pk_mul_f32 v[158:159], v[158:159], v[14:15]
	v_pk_mul_f32 v[160:161], v[160:161], v[16:17]
	v_pk_mul_f32 v[162:163], v[162:163], v[6:7]
	v_pk_mul_f32 v[164:165], v[164:165], v[8:9]
	v_pk_mul_f32 v[158:159], v[158:159], v[10:11]
	v_pk_mul_f32 v[160:161], v[160:161], v[12:13]
	v_pk_mul_f32 v[162:163], v[162:163], v[2:3]
	v_pk_mul_f32 v[164:165], v[164:165], v[4:5]
	v_cvt_pk_bf16_f32 v166, v158, v159
	v_cvt_pk_bf16_f32 v167, v160, v161
	v_cvt_pk_bf16_f32 v168, v162, v163
	v_cvt_pk_bf16_f32 v169, v164, v165
	global_store_dwordx4 v1, v[166:169], s[0:1]
	s_andn2_b64 vcc, exec, s[76:77]
	s_cbranch_vccnz .LBB0_104
; __device__ __forceinline__ void rsv_load(float (&rsv)[2][4], const GD& g, const pg8::Unit& u, int wr, int fr) {
;     if (g.f2) { const int rg = (u.z / g.nz2) * g.ro1 + u.pm * 256 + wr * 64 + fr;
; #pragma unroll
;         for (int ai = 0; ai < 2; ++ai)
; #pragma unroll
;             for (int m = 0; m < 4; ++m) rsv[ai][m] = g.f2[rg + ai * 128 + m * 16]; }
	s_and_b64 vcc, exec, s[6:7]
	s_cbranch_vccnz .LBB0_137
	s_ashr_i32 s0, s26, 31
	v_readlane_b32 s1, v255, 2
	s_xor_b32 s0, s0, s1
	s_abs_i32 s1, s26
	v_readlane_b32 s2, v255, 6
	s_mul_hi_u32 s2, s1, s2
	s_mul_i32 s3, s2, s24
	s_sub_i32 s1, s1, s3
	s_add_i32 s3, s2, 1
	s_sub_i32 s4, s1, s24
	s_cmp_ge_u32 s1, s24
	s_cselect_b32 s2, s3, s2
	s_cselect_b32 s1, s4, s1
	s_add_i32 s3, s2, 1
	s_cmp_ge_u32 s1, s24
	s_cselect_b32 s1, s3, s2
	s_xor_b32 s1, s1, s0
	s_sub_i32 s0, s1, s0
	v_readlane_b32 s1, v254, 59
	s_mul_i32 s0, s0, s1
	s_lshl_b32 s1, s28, 8
	s_add_i32 s0, s0, s1
	v_add_u32_e32 v2, s0, v144
	v_readlane_b32 s0, v254, 52
	v_ashrrev_i32_e32 v3, 31, v2
	v_readlane_b32 s1, v254, 53
	s_nop 1
	v_lshl_add_u64 v[2:3], v[2:3], 2, s[0:1]
	flat_load_dword v145, v[2:3]
	flat_load_dword v146, v[2:3] offset:64
	flat_load_dword v147, v[2:3] offset:128
	flat_load_dword v148, v[2:3] offset:192
	flat_load_dword v149, v[2:3] offset:512
	flat_load_dword v150, v[2:3] offset:576
	flat_load_dword v151, v[2:3] offset:640
	flat_load_dword v152, v[2:3] offset:704
